# v57 + P1 SwiGLU epilogue: per-row rstd values preloaded into v248-255 before the unit's K loop; epilogue entry vmcnt(0) removed (next unit's prefetch DMAs stay in flight through the epilogue); vgpr 25
# baseline (speedup 1.0000x reference)
.LBB0_421:
	s_ashr_i32 s21, s20, 31
	s_lshl_b64 s[22:23], s[20:21], 15
	v_readlane_b32 s9, v245, 12
	s_add_u32 s22, s9, s22
	v_readlane_b32 s9, v245, 13
	s_addc_u32 s23, s9, s23
	s_and_b64 s[24:25], s[6:7], exec
	s_cselect_b32 s9, s23, s31
	s_cselect_b32 s21, s22, s30
	s_ashr_i32 s19, s18, 31
	s_lshl_b64 s[24:25], s[18:19], 15
	s_add_u32 s24, s4, s24
	s_addc_u32 s25, s5, s25
	s_and_b64 s[34:35], s[6:7], exec
	s_cselect_b32 s19, s25, s29
	s_cselect_b32 s50, s24, s28
	s_add_u32 s51, s28, 0x700000
	s_addc_u32 s52, s29, 0
	s_add_u32 s28, s30, 0x104000
	v_mov_b32_e32 v2, 0
	s_addc_u32 s29, s31, 0
	s_mov_b32 s53, -2
	v_mov_b32_e32 v3, v2
	v_mov_b32_e32 v4, v2
	v_mov_b32_e32 v5, v2
	v_mov_b32_e32 v6, v2
	v_mov_b32_e32 v7, v2
	v_mov_b32_e32 v8, v2
	v_mov_b32_e32 v9, v2
	v_mov_b32_e32 v18, v2
	v_mov_b32_e32 v19, v2
	v_mov_b32_e32 v20, v2
	v_mov_b32_e32 v21, v2
	v_mov_b32_e32 v22, v2
	v_mov_b32_e32 v23, v2
	v_mov_b32_e32 v24, v2
	v_mov_b32_e32 v25, v2
	s_waitcnt vmcnt(0)
	v_mov_b64_e32 v[10:11], 0
	v_mov_b64_e32 v[12:13], 0
	v_mov_b64_e32 v[14:15], 0
	v_mov_b64_e32 v[16:17], 0
	v_mov_b64_e32 v[26:27], 0
	v_mov_b64_e32 v[28:29], 0
	v_mov_b64_e32 v[30:31], 0
	v_mov_b64_e32 v[32:33], 0
	v_mov_b64_e32 v[34:35], 0
	v_mov_b64_e32 v[36:37], 0
	v_mov_b64_e32 v[38:39], 0
	v_mov_b64_e32 v[40:41], 0
	v_mov_b64_e32 v[42:43], 0
	v_mov_b64_e32 v[44:45], 0
	v_mov_b64_e32 v[46:47], 0
	v_mov_b64_e32 v[48:49], 0
	v_mov_b64_e32 v[50:51], 0
	v_mov_b64_e32 v[52:53], 0
	v_mov_b64_e32 v[54:55], 0
	v_mov_b64_e32 v[56:57], 0
	v_mov_b64_e32 v[58:59], 0
	v_mov_b64_e32 v[60:61], 0
	v_mov_b64_e32 v[62:63], 0
	v_mov_b64_e32 v[64:65], 0
	v_mov_b64_e32 v[66:67], 0
	v_mov_b64_e32 v[68:69], 0
	v_mov_b64_e32 v[70:71], 0
	v_mov_b64_e32 v[72:73], 0
	v_mov_b64_e32 v[74:75], 0
	v_mov_b64_e32 v[76:77], 0
	v_mov_b64_e32 v[78:79], 0
	v_mov_b64_e32 v[80:81], 0
	v_mov_b64_e32 v[82:83], 0
	v_mov_b64_e32 v[84:85], 0
	v_mov_b64_e32 v[86:87], 0
	v_mov_b64_e32 v[88:89], 0
	v_mov_b64_e32 v[90:91], 0
	v_mov_b64_e32 v[92:93], 0
	v_mov_b64_e32 v[94:95], 0
	v_mov_b64_e32 v[96:97], 0
	v_mov_b64_e32 v[98:99], 0
	v_mov_b64_e32 v[100:101], 0
	v_mov_b64_e32 v[102:103], 0
	v_mov_b64_e32 v[104:105], 0
	v_mov_b64_e32 v[106:107], 0
	v_mov_b64_e32 v[108:109], 0
	v_mov_b64_e32 v[110:111], 0
	v_mov_b64_e32 v[112:113], 0
	v_mov_b64_e32 v[114:115], 0
	v_mov_b64_e32 v[116:117], 0
	v_mov_b64_e32 v[118:119], 0
	v_mov_b64_e32 v[120:121], 0
	v_mov_b64_e32 v[122:123], 0
	v_mov_b64_e32 v[124:125], 0
	v_mov_b64_e32 v[126:127], 0
	v_mov_b64_e32 v[128:129], 0
	v_and_or_b32 v246, v151, 15, s42
	v_lshl_add_u32 v246, s8, 8, v246
	v_ashrrev_i32_e32 v247, 31, v246
	v_readlane_b32 s98, v245, 16
	v_readlane_b32 s99, v245, 17
	s_nop 1
	v_lshl_add_u64 v[246:247], v[246:247], 2, s[98:99]
	global_load_dword v248, v[246:247], off
	global_load_dword v249, v[246:247], off offset:64
	global_load_dword v250, v[246:247], off offset:128
	global_load_dword v251, v[246:247], off offset:192
	global_load_dword v252, v[246:247], off offset:512
	global_load_dword v253, v[246:247], off offset:576
	global_load_dword v254, v[246:247], off offset:640
	global_load_dword v255, v[246:247], off offset:704

.LBB0_425:
	v_mov_b32_e32 v148, v151
	v_cndmask_b32_e64 v149, 0, 1, s[10:11]
	v_and_or_b32 v146, v148, 15, s42
	v_lshl_add_u32 v146, s8, 8, v146
	v_ashrrev_i32_e32 v147, 31, v146
	v_mov_b32_e32 v150, 1.0
	v_cmp_ne_u32_e64 s[8:9], 1, v149
	s_andn2_b64 vcc, exec, s[10:11]
	v_mov_b32_e32 v152, 1.0
	s_cbranch_vccnz .LBB0_427
	v_readlane_b32 s28, v245, 16
	v_readlane_b32 s29, v245, 17
	s_nop 1
	v_lshl_add_u64 v[158:159], v[146:147], 2, s[28:29]
	v_mov_b32_e32 v152, v248
	v_mov_b32_e32 v187, v249
	v_mov_b32_e32 v188, v250
	v_mov_b32_e32 v189, v251
	v_mov_b32_e32 v190, v252
	v_mov_b32_e32 v191, v253
	v_mov_b32_e32 v192, v254
	v_mov_b32_e32 v193, v255
.LBB0_427:
	v_pk_mul_f32 v[126:127], v[126:127], v[152:153] op_sel_hi:[1,0]
	v_lshlrev_b64 v[158:159], 7, v[146:147]
	v_mul_f32_e32 v147, 0xbfb8aa3b, v126
	v_exp_f32_e32 v147, v147
	v_mul_f32_e32 v157, 0xbfb8aa3b, v127
	v_exp_f32_e32 v157, v157
	v_pk_mul_f32 v[160:161], v[116:117], v[152:153] op_sel_hi:[1,0]
	v_add_f32_e32 v116, 1.0, v147
	v_rcp_f32_e32 v147, v116
	v_add_f32_e32 v116, 1.0, v157
	v_pk_mul_f32 v[128:129], v[128:129], v[152:153] op_sel_hi:[1,0]
	v_pk_mul_f32 v[118:119], v[118:119], v[152:153] op_sel_hi:[1,0]
	v_rcp_f32_e32 v157, v116
	v_pk_mul_f32 v[116:117], v[114:115], v[152:153] op_sel_hi:[1,0]
	v_mul_f32_e32 v114, v126, v147
	v_mul_f32_e32 v114, v118, v114
	v_mul_f32_e32 v118, 0xbfb8aa3b, v128
	v_mul_f32_e32 v126, 0xbfb8aa3b, v129
	v_exp_f32_e32 v118, v118
	v_exp_f32_e32 v126, v126
	v_mul_f32_e32 v115, v127, v157
	v_mul_f32_e32 v115, v119, v115
	v_add_f32_e32 v118, 1.0, v118
	v_add_f32_e32 v119, 1.0, v126
	v_rcp_f32_e32 v118, v118
	v_rcp_f32_e32 v119, v119
	v_pk_mul_f32 v[122:123], v[122:123], v[152:153] op_sel_hi:[1,0]
	v_pk_mul_f32 v[120:121], v[120:121], v[152:153] op_sel_hi:[1,0]
	v_cvt_pk_bf16_f32 v114, v114, v115
	v_mul_f32_e32 v115, v128, v118
	v_mul_f32_e32 v118, v129, v119
	v_mul_f32_e32 v119, 0xbfb8aa3b, v122
	v_mul_f32_e32 v115, v120, v115
	v_exp_f32_e32 v119, v119
	v_mul_f32_e32 v120, 0xbfb8aa3b, v123
	v_exp_f32_e32 v120, v120
	v_pk_mul_f32 v[124:125], v[124:125], v[152:153] op_sel_hi:[1,0]
	v_add_f32_e32 v119, 1.0, v119
	v_rcp_f32_e32 v119, v119
	v_add_f32_e32 v120, 1.0, v120
	v_rcp_f32_e32 v120, v120
	v_mul_f32_e32 v118, v121, v118
	v_cvt_pk_bf16_f32 v115, v115, v118
	v_mul_f32_e32 v118, v122, v119
	v_mul_f32_e32 v119, 0xbfb8aa3b, v124
	v_mul_f32_e32 v116, v116, v118
	v_mul_f32_e32 v118, v123, v120
	v_exp_f32_e32 v119, v119
	v_mul_f32_e32 v120, 0xbfb8aa3b, v125
	v_exp_f32_e32 v120, v120
	s_lshl_b32 s19, s26, 7
	s_or_b32 s19, s19, s43
	s_ashr_i32 s28, s19, 6
	v_mul_f32_e32 v117, v117, v118
	v_add_f32_e32 v118, 1.0, v119
	v_lshrrev_b32_e32 v148, 1, v148
	s_ashr_i32 s29, s28, 31
	v_rcp_f32_e32 v118, v118
	v_add_f32_e32 v119, 1.0, v120
	s_lshl_b64 s[28:29], s[28:29], 19
	v_and_or_b32 v148, v148, 24, s46
	v_rcp_f32_e32 v119, v119
	v_or_b32_e32 v148, s28, v148
	v_mov_b32_e32 v149, s29
	v_readlane_b32 s28, v245, 14
	v_readlane_b32 s29, v245, 15
	v_cvt_pk_bf16_f32 v116, v116, v117
	v_mul_f32_e32 v117, v124, v118
	v_mul_f32_e32 v117, v160, v117
	v_lshl_add_u64 v[158:159], s[28:29], 0, v[158:159]
	v_lshl_add_u64 v[158:159], v[148:149], 1, v[158:159]
	v_mul_f32_e32 v118, v125, v119
	v_mul_f32_e32 v118, v161, v118
	v_cvt_pk_bf16_f32 v117, v117, v118
	global_store_dwordx4 v[158:159], v[114:117], off
	s_and_b64 vcc, exec, s[8:9]
	s_nop 0
	v_or_b32_e32 v114, 16, v146
	v_ashrrev_i32_e32 v115, 31, v114
	s_cbranch_vccnz .LBB0_429
	v_readlane_b32 s28, v245, 16
	v_readlane_b32 s29, v245, 17
	s_nop 1
	v_lshl_add_u64 v[116:117], v[114:115], 2, s[28:29]
	v_mov_b32_e32 v150, v187
